# attention: lazy-rescale decision branch taken from v_cmp + s_or directly (ballot cndmask/cmp removed)
# speedup vs baseline: 1.0027x; 1.0027x over previous
; template <int MODE> ...
;     ...
; #pragma unroll
;     for (int tt = 0; tt < 2; ++tt)
; #pragma unroll
;       for (int hh = 0; hh < 2; ++hh) {
;         const float nb = nbias[tt][hh];
; #pragma unroll
;         for (int kh = 0; kh < 2; ++kh)
; #pragma unroll
;           for (int t = 0; t < 2; ++t) S[kh][tt][hh][t] = S[kh][tt][hh][t] * c1 + nb;
;       }
;     {
;       float mxq[2][2];
;       bool need = first;
; #pragma unroll
;       for (int tt = 0; tt < 2; ++tt)
; #pragma unroll
;         for (int hh = 0; hh < 2; ++hh) {
;           const float m0 = fmaxf(fmaxf(S[0][tt][hh][0][0], S[0][tt][hh][0][1]), S[0][tt][hh][0][2]);
;           const float m1 = fmaxf(fmaxf(S[0][tt][hh][1][0], S[0][tt][hh][1][1]), S[0][tt][hh][1][2]);
;           const float m2 = fmaxf(fmaxf(S[1][tt][hh][0][0], S[1][tt][hh][0][1]), S[1][tt][hh][0][2]);
;           const float m3 = fmaxf(fmaxf(S[1][tt][hh][1][0], S[1][tt][hh][1][1]), S[1][tt][hh][1][2]);
;           const float m4 = fmaxf(fmaxf(S[0][tt][hh][0][3], S[0][tt][hh][1][3]), m0);
;           const float m5 = fmaxf(fmaxf(S[1][tt][hh][0][3], S[1][tt][hh][1][3]), m1);
;           mxq[tt][hh] = fmaxf(fmaxf(m2, m3), fmaxf(m4, m5));
;           need = need || (mxq[tt][hh] > 8.f);
;         }
;       if (__builtin_amdgcn_ballot_w64(need) != 0) {
.LBB0_871:
	v_pk_fma_f32 v[196:197], v[158:159], s[28:29], v[180:181] op_sel_hi:[1,0,0]
	v_pk_fma_f32 v[198:199], v[156:157], s[28:29], v[180:181] op_sel_hi:[1,0,0]
	v_pk_fma_f32 v[190:191], v[162:163], s[28:29], v[180:181] op_sel_hi:[1,0,0]
	v_pk_fma_f32 v[192:193], v[160:161], s[28:29], v[180:181] op_sel_hi:[1,0,0]
	v_pk_fma_f32 v[170:171], v[170:171], s[28:29], v[180:181] op_sel_hi:[1,0,0]
	v_pk_fma_f32 v[166:167], v[166:167], s[28:29], v[180:181] op_sel_hi:[1,0,0]
	v_pk_fma_f32 v[200:201], v[146:147], s[28:29], v[178:179] op_sel_hi:[1,0,0]
	v_pk_fma_f32 v[146:147], v[148:149], s[28:29], v[178:179] op_sel_hi:[1,0,0]
	v_pk_fma_f32 v[148:149], v[138:139], s[28:29], v[2:3] op_sel_hi:[1,0,0]
	v_pk_fma_f32 v[138:139], v[108:109], s[28:29], v[176:177] op_sel_hi:[1,0,0]
	v_max3_f32 v109, v198, v199, v196
	v_pk_fma_f32 v[168:169], v[168:169], s[28:29], v[180:181] op_sel_hi:[1,0,0]
	v_pk_fma_f32 v[164:165], v[164:165], s[28:29], v[180:181] op_sel_hi:[1,0,0]
	v_pk_fma_f32 v[204:205], v[142:143], s[28:29], v[178:179] op_sel_hi:[1,0,0]
	v_pk_fma_f32 v[206:207], v[140:141], s[28:29], v[178:179] op_sel_hi:[1,0,0]
	v_pk_fma_f32 v[142:143], v[152:153], s[28:29], v[178:179] op_sel_hi:[1,0,0]
	v_pk_fma_f32 v[152:153], v[134:135], s[28:29], v[2:3] op_sel_hi:[1,0,0]
	v_pk_fma_f32 v[134:135], v[112:113], s[28:29], v[176:177] op_sel_hi:[1,0,0]
	v_max3_f32 v108, v192, v193, v190
	v_max_f32_e32 v112, v191, v197
	v_max3_f32 v109, v171, v167, v109
	v_pk_fma_f32 v[202:203], v[144:145], s[28:29], v[178:179] op_sel_hi:[1,0,0]
	v_pk_fma_f32 v[140:141], v[154:155], s[28:29], v[178:179] op_sel_hi:[1,0,0]
	v_pk_fma_f32 v[144:145], v[150:151], s[28:29], v[178:179] op_sel_hi:[1,0,0]
	v_pk_fma_f32 v[150:151], v[136:137], s[28:29], v[2:3] op_sel_hi:[1,0,0]
	v_pk_fma_f32 v[136:137], v[110:111], s[28:29], v[176:177] op_sel_hi:[1,0,0]
	v_max3_f32 v110, v168, v169, v170
	v_max3_f32 v111, v164, v165, v166
	v_max3_f32 v108, v112, v108, v109
	v_max3_f32 v109, v206, v207, v204
	v_pk_fma_f32 v[126:127], v[126:127], s[28:29], v[2:3] op_sel_hi:[1,0,0]
	v_pk_fma_f32 v[124:125], v[124:125], s[28:29], v[2:3] op_sel_hi:[1,0,0]
	v_max3_f32 v111, v110, v111, v108
	v_max3_f32 v108, v202, v203, v200
	v_max_f32_e32 v113, v201, v205
	v_max3_f32 v109, v141, v145, v109
	v_pk_fma_f32 v[130:131], v[130:131], s[28:29], v[2:3] op_sel_hi:[1,0,0]
	v_pk_fma_f32 v[128:129], v[128:129], s[28:29], v[2:3] op_sel_hi:[1,0,0]
	v_max3_f32 v110, v142, v143, v140
	v_max3_f32 v112, v146, v147, v144
	v_max3_f32 v108, v113, v108, v109
	v_max3_f32 v109, v124, v125, v126
	v_pk_fma_f32 v[154:155], v[132:133], s[28:29], v[2:3] op_sel_hi:[1,0,0]
	v_pk_fma_f32 v[132:133], v[114:115], s[28:29], v[176:177] op_sel_hi:[1,0,0]
	v_max3_f32 v110, v110, v112, v108
	v_max3_f32 v108, v128, v129, v130
	v_max_f32_e32 v114, v131, v127
	v_max3_f32 v109, v149, v153, v109
	v_max3_f32 v112, v150, v151, v148
	v_max3_f32 v113, v154, v155, v152
	v_max3_f32 v108, v114, v108, v109
	v_pk_fma_f32 v[156:157], v[122:123], s[28:29], v[176:177] op_sel_hi:[1,0,0]
	v_pk_fma_f32 v[160:161], v[118:119], s[28:29], v[176:177] op_sel_hi:[1,0,0]
	v_max3_f32 v109, v112, v113, v108
	v_max3_f32 v113, v138, v139, v136
	v_pk_fma_f32 v[158:159], v[120:121], s[28:29], v[176:177] op_sel_hi:[1,0,0]
	v_pk_fma_f32 v[162:163], v[116:117], s[28:29], v[176:177] op_sel_hi:[1,0,0]
	v_max3_f32 v108, v134, v135, v132
	v_max_f32_e32 v116, v133, v137
	v_max3_f32 v113, v157, v161, v113
	v_max3_f32 v114, v158, v159, v156
	v_max3_f32 v115, v162, v163, v160
	v_max3_f32 v108, v116, v108, v113
	v_max3_f32 v112, v109, v110, v111
	v_max3_f32 v108, v114, v115, v108
	v_max_f32_e32 v112, v108, v112
	s_mov_b32 s23, 0x41000000
	v_cmp_lt_f32_e32 vcc, s23, v112
	s_or_b64 vcc, vcc, s[42:43]
	s_cbranch_vccz .LBB0_873
; template <int MODE> ...
;     ...
; #pragma unroll
;         for (int tt = 0; tt < 2; ++tt)
; #pragma unroll
;           for (int hh = 0; hh < 2; ++hh) {
;             float mx = mxq[tt][hh];
;             mx = fmaxf(mx, __shfl_xor(mx, 16));
;             mx = fmaxf(mx, __shfl_xor(mx, 32));
;             const float d = (mx == -INFINITY) ? 0.f : (first ? mx : fmaxf(mx, 0.f));
;             const float alpha = __builtin_amdgcn_exp2f(-d);
;             lsum[tt][hh] *= alpha;
;             nbias[tt][hh] -= d;
; #pragma unroll
;             for (int dt = 0; dt < 4; ++dt)
; #pragma unroll
;               for (int j = 0; j < 4; ++j) O[tt][hh][dt][j] *= alpha;
; #pragma unroll
;             for (int kh = 0; kh < 2; ++kh)
; #pragma unroll
;               for (int t = 0; t < 2; ++t) S[kh][tt][hh][t] = S[kh][tt][hh][t] - d;
;           }
	v_and_b32_e32 v113, 64, v226
	v_xor_b32_e32 v112, 16, v226
	v_add_u32_e32 v113, 64, v113
	v_cmp_lt_i32_e32 vcc, v112, v113
	s_nop 1
	v_cndmask_b32_e32 v112, v226, v112, vcc
	v_lshlrev_b32_e32 v114, 2, v112
	v_xor_b32_e32 v112, 32, v226
	v_cmp_lt_i32_e32 vcc, v112, v113
	s_nop 1
	v_cndmask_b32_e32 v112, v226, v112, vcc
	v_lshlrev_b32_e32 v115, 2, v112
	ds_bpermute_b32 v112, v114, v111
	v_max_f32_e32 v111, v111, v111
	s_waitcnt lgkmcnt(0)
	v_max_f32_e32 v112, v112, v112
	v_max_f32_e32 v111, v111, v112
	ds_bpermute_b32 v112, v115, v111
	s_waitcnt lgkmcnt(0)
	v_max_f32_e32 v112, v112, v112
	v_max_f32_e32 v111, v111, v112
	v_max_f32_e32 v112, 0, v111
	v_cndmask_b32_e64 v112, v112, v111, s[42:43]
	v_cmp_neq_f32_e32 vcc, s20, v111
	s_nop 1
	v_cndmask_b32_e32 v111, 0, v112, vcc
	v_exp_f32_e64 v112, -v111
	v_sub_f32_e32 v180, v180, v111
	v_sub_f32_e32 v192, v192, v111
	v_sub_f32_e32 v193, v193, v111
	v_sub_f32_e32 v190, v190, v111
	v_sub_f32_e32 v191, v191, v111
	v_sub_f32_e32 v198, v198, v111
	v_sub_f32_e32 v199, v199, v111
	v_sub_f32_e32 v196, v196, v111
	v_sub_f32_e32 v197, v197, v111
	v_sub_f32_e32 v168, v168, v111
	v_sub_f32_e32 v169, v169, v111
	v_sub_f32_e32 v170, v170, v111
	v_sub_f32_e32 v171, v171, v111
	v_sub_f32_e32 v164, v164, v111
	v_sub_f32_e32 v165, v165, v111
	v_sub_f32_e32 v166, v166, v111
	v_sub_f32_e32 v167, v167, v111
	ds_bpermute_b32 v111, v114, v110
	v_max_f32_e32 v110, v110, v110
	v_pk_mul_f32 v[54:55], v[54:55], v[112:113] op_sel_hi:[1,0]
	v_pk_mul_f32 v[52:53], v[52:53], v[112:113] op_sel_hi:[1,0]
	v_pk_mul_f32 v[62:63], v[62:63], v[112:113] op_sel_hi:[1,0]
	s_waitcnt lgkmcnt(0)
	v_max_f32_e32 v111, v111, v111
	v_max_f32_e32 v110, v110, v111
	ds_bpermute_b32 v111, v115, v110
	v_pk_mul_f32 v[60:61], v[60:61], v[112:113] op_sel_hi:[1,0]
	v_pk_mul_f32 v[58:59], v[58:59], v[112:113] op_sel_hi:[1,0]
	v_pk_mul_f32 v[56:57], v[56:57], v[112:113] op_sel_hi:[1,0]
	v_pk_mul_f32 v[66:67], v[66:67], v[112:113] op_sel_hi:[1,0]
	s_waitcnt lgkmcnt(0)
	v_max_f32_e32 v111, v111, v111
	v_max_f32_e32 v110, v110, v111
	v_max_f32_e32 v111, 0, v110
	v_cndmask_b32_e64 v111, v111, v110, s[42:43]
	v_cmp_neq_f32_e32 vcc, s20, v110
	v_pk_mul_f32 v[64:65], v[64:65], v[112:113] op_sel_hi:[1,0]
	s_nop 0
	v_cndmask_b32_e32 v111, 0, v111, vcc
	v_exp_f32_e64 v113, -v111
	v_sub_f32_e32 v178, v178, v111
	v_sub_f32_e32 v202, v202, v111
	v_sub_f32_e32 v203, v203, v111
	v_mov_b32_e32 v110, v113
	v_pk_mul_f32 v[46:47], v[46:47], v[110:111] op_sel_hi:[1,0]
	v_pk_mul_f32 v[44:45], v[44:45], v[110:111] op_sel_hi:[1,0]
	v_pk_mul_f32 v[42:43], v[42:43], v[110:111] op_sel_hi:[1,0]
	v_pk_mul_f32 v[40:41], v[40:41], v[110:111] op_sel_hi:[1,0]
	v_pk_mul_f32 v[38:39], v[38:39], v[110:111] op_sel_hi:[1,0]
	v_pk_mul_f32 v[36:37], v[36:37], v[110:111] op_sel_hi:[1,0]
	v_pk_mul_f32 v[50:51], v[50:51], v[110:111] op_sel_hi:[1,0]
	v_pk_mul_f32 v[48:49], v[48:49], v[110:111] op_sel_hi:[1,0]
	ds_bpermute_b32 v110, v114, v109
	v_max_f32_e32 v109, v109, v109
	v_sub_f32_e32 v200, v200, v111
	v_sub_f32_e32 v201, v201, v111
	v_sub_f32_e32 v206, v206, v111
	s_waitcnt lgkmcnt(0)
	v_max_f32_e32 v110, v110, v110
	v_max_f32_e32 v109, v109, v110
	ds_bpermute_b32 v110, v115, v109
	v_sub_f32_e32 v207, v207, v111
	v_sub_f32_e32 v204, v204, v111
	v_sub_f32_e32 v205, v205, v111
	v_sub_f32_e32 v142, v142, v111
	s_waitcnt lgkmcnt(0)
	v_max_f32_e32 v110, v110, v110
	v_max_f32_e32 v109, v109, v110
	v_max_f32_e32 v110, 0, v109
	v_cndmask_b32_e64 v110, v110, v109, s[42:43]
	v_cmp_neq_f32_e32 vcc, s20, v109
	v_sub_f32_e32 v143, v143, v111
	v_sub_f32_e32 v140, v140, v111
	v_cndmask_b32_e32 v109, 0, v110, vcc
	v_exp_f32_e64 v110, -v109
	v_sub_f32_e32 v2, v2, v109
	v_sub_f32_e32 v128, v128, v109
	v_sub_f32_e32 v129, v129, v109
	v_sub_f32_e32 v130, v130, v109
	v_sub_f32_e32 v131, v131, v109
	v_sub_f32_e32 v124, v124, v109
	v_sub_f32_e32 v125, v125, v109
	v_sub_f32_e32 v126, v126, v109
	v_sub_f32_e32 v127, v127, v109
	v_sub_f32_e32 v150, v150, v109
	v_sub_f32_e32 v151, v151, v109
	v_sub_f32_e32 v148, v148, v109
	v_sub_f32_e32 v149, v149, v109
	v_sub_f32_e32 v154, v154, v109
	v_sub_f32_e32 v155, v155, v109
	v_sub_f32_e32 v152, v152, v109
	v_sub_f32_e32 v153, v153, v109
	ds_bpermute_b32 v109, v114, v108
	v_max_f32_e32 v108, v108, v108
	v_sub_f32_e32 v141, v141, v111
	v_sub_f32_e32 v146, v146, v111
	v_sub_f32_e32 v147, v147, v111
	s_waitcnt lgkmcnt(0)
	v_max_f32_e32 v109, v109, v109
	v_max_f32_e32 v108, v108, v109
	ds_bpermute_b32 v109, v115, v108
	v_sub_f32_e32 v144, v144, v111
	v_sub_f32_e32 v145, v145, v111
	v_pk_mul_f32 v[34:35], v[34:35], v[110:111] op_sel_hi:[1,0]
	v_pk_mul_f32 v[32:33], v[32:33], v[110:111] op_sel_hi:[1,0]
	s_waitcnt lgkmcnt(0)
	v_max_f32_e32 v109, v109, v109
	v_max_f32_e32 v108, v108, v109
	v_max_f32_e32 v109, 0, v108
	v_cndmask_b32_e64 v109, v109, v108, s[42:43]
	v_cmp_neq_f32_e32 vcc, s20, v108
	v_pk_mul_f32 v[30:31], v[30:31], v[110:111] op_sel_hi:[1,0]
	v_pk_mul_f32 v[28:29], v[28:29], v[110:111] op_sel_hi:[1,0]
	v_cndmask_b32_e32 v109, 0, v109, vcc
	v_pk_mul_f32 v[26:27], v[26:27], v[110:111] op_sel_hi:[1,0]
	v_pk_mul_f32 v[24:25], v[24:25], v[110:111] op_sel_hi:[1,0]
	v_pk_mul_f32 v[22:23], v[22:23], v[110:111] op_sel_hi:[1,0]
	v_pk_mul_f32 v[20:21], v[20:21], v[110:111] op_sel_hi:[1,0]
	v_exp_f32_e64 v111, -v109
	v_pk_mul_f32 v[188:189], v[188:189], v[112:113]
	v_sub_f32_e32 v176, v176, v109
	v_sub_f32_e32 v134, v134, v109
	v_mov_b32_e32 v108, v111
	v_pk_mul_f32 v[186:187], v[186:187], v[110:111]
	v_pk_mul_f32 v[18:19], v[18:19], v[108:109] op_sel_hi:[1,0]
	v_pk_mul_f32 v[16:17], v[16:17], v[108:109] op_sel_hi:[1,0]
	v_pk_mul_f32 v[14:15], v[14:15], v[108:109] op_sel_hi:[1,0]
	v_pk_mul_f32 v[12:13], v[12:13], v[108:109] op_sel_hi:[1,0]
	v_pk_mul_f32 v[10:11], v[10:11], v[108:109] op_sel_hi:[1,0]
	v_pk_mul_f32 v[8:9], v[8:9], v[108:109] op_sel_hi:[1,0]
	v_pk_mul_f32 v[6:7], v[6:7], v[108:109] op_sel_hi:[1,0]
	v_pk_mul_f32 v[4:5], v[4:5], v[108:109] op_sel_hi:[1,0]
	v_sub_f32_e32 v135, v135, v109
	v_sub_f32_e32 v132, v132, v109
	v_sub_f32_e32 v133, v133, v109
	v_sub_f32_e32 v138, v138, v109
	v_sub_f32_e32 v139, v139, v109
	v_sub_f32_e32 v136, v136, v109
	v_sub_f32_e32 v137, v137, v109
	v_sub_f32_e32 v158, v158, v109
	v_sub_f32_e32 v159, v159, v109
	v_sub_f32_e32 v156, v156, v109
	v_sub_f32_e32 v157, v157, v109
	v_sub_f32_e32 v162, v162, v109
	v_sub_f32_e32 v163, v163, v109
	v_sub_f32_e32 v160, v160, v109
	v_sub_f32_e32 v161, v161, v109

; template <int MODE> ...
;     ...
; #pragma unroll
;     for (int tt = 0; tt < 2; ++tt)
; #pragma unroll
;       for (int hh = 0; hh < 2; ++hh) {
;         const float nb = nbias[tt][hh];
; #pragma unroll
;         for (int kh = 0; kh < 2; ++kh)
; #pragma unroll
;           for (int t = 0; t < 2; ++t) S[kh][tt][hh][t] = S[kh][tt][hh][t] * c1 + nb;
;       }
;     {
;       float mxq[2][2];
;       bool need = first;
; #pragma unroll
;       for (int tt = 0; tt < 2; ++tt)
; #pragma unroll
;         for (int hh = 0; hh < 2; ++hh) {
;           const float m0 = fmaxf(fmaxf(S[0][tt][hh][0][0], S[0][tt][hh][0][1]), S[0][tt][hh][0][2]);
;           const float m1 = fmaxf(fmaxf(S[0][tt][hh][1][0], S[0][tt][hh][1][1]), S[0][tt][hh][1][2]);
;           const float m2 = fmaxf(fmaxf(S[1][tt][hh][0][0], S[1][tt][hh][0][1]), S[1][tt][hh][0][2]);
;           const float m3 = fmaxf(fmaxf(S[1][tt][hh][1][0], S[1][tt][hh][1][1]), S[1][tt][hh][1][2]);
;           const float m4 = fmaxf(fmaxf(S[0][tt][hh][0][3], S[0][tt][hh][1][3]), m0);
;           const float m5 = fmaxf(fmaxf(S[1][tt][hh][0][3], S[1][tt][hh][1][3]), m1);
;           mxq[tt][hh] = fmaxf(fmaxf(m2, m3), fmaxf(m4, m5));
;           need = need || (mxq[tt][hh] > 8.f);
;         }
;       if (__builtin_amdgcn_ballot_w64(need) != 0) {
.LBB0_891:
	v_pk_fma_f32 v[178:179], v[140:141], s[36:37], v[162:163] op_sel_hi:[1,0,0]
	v_pk_fma_f32 v[180:181], v[138:139], s[36:37], v[162:163] op_sel_hi:[1,0,0]
	v_pk_fma_f32 v[174:175], v[144:145], s[36:37], v[162:163] op_sel_hi:[1,0,0]
	v_pk_fma_f32 v[176:177], v[142:143], s[36:37], v[162:163] op_sel_hi:[1,0,0]
	v_pk_fma_f32 v[152:153], v[152:153], s[36:37], v[162:163] op_sel_hi:[1,0,0]
	v_pk_fma_f32 v[148:149], v[148:149], s[36:37], v[162:163] op_sel_hi:[1,0,0]
	v_pk_fma_f32 v[182:183], v[128:129], s[36:37], v[164:165] op_sel_hi:[1,0,0]
	v_pk_fma_f32 v[128:129], v[130:131], s[36:37], v[164:165] op_sel_hi:[1,0,0]
	v_pk_fma_f32 v[130:131], v[120:121], s[36:37], v[160:161] op_sel_hi:[1,0,0]
	v_pk_fma_f32 v[120:121], v[90:91], s[36:37], v[158:159] op_sel_hi:[1,0,0]
	v_max3_f32 v91, v180, v181, v178
	v_pk_fma_f32 v[150:151], v[150:151], s[36:37], v[162:163] op_sel_hi:[1,0,0]
	v_pk_fma_f32 v[146:147], v[146:147], s[36:37], v[162:163] op_sel_hi:[1,0,0]
	v_pk_fma_f32 v[186:187], v[124:125], s[36:37], v[164:165] op_sel_hi:[1,0,0]
	v_pk_fma_f32 v[188:189], v[122:123], s[36:37], v[164:165] op_sel_hi:[1,0,0]
	v_pk_fma_f32 v[124:125], v[134:135], s[36:37], v[164:165] op_sel_hi:[1,0,0]
	v_pk_fma_f32 v[134:135], v[112:113], s[36:37], v[160:161] op_sel_hi:[1,0,0]
	v_pk_fma_f32 v[112:113], v[94:95], s[36:37], v[158:159] op_sel_hi:[1,0,0]
	v_max3_f32 v90, v176, v177, v174
	v_max_f32_e32 v94, v175, v179
	v_max3_f32 v91, v153, v149, v91
	v_pk_fma_f32 v[184:185], v[126:127], s[36:37], v[164:165] op_sel_hi:[1,0,0]
	v_pk_fma_f32 v[122:123], v[136:137], s[36:37], v[164:165] op_sel_hi:[1,0,0]
	v_pk_fma_f32 v[126:127], v[132:133], s[36:37], v[164:165] op_sel_hi:[1,0,0]
	v_pk_fma_f32 v[132:133], v[118:119], s[36:37], v[160:161] op_sel_hi:[1,0,0]
	v_pk_fma_f32 v[118:119], v[92:93], s[36:37], v[158:159] op_sel_hi:[1,0,0]
	v_max3_f32 v92, v150, v151, v152
	v_max3_f32 v93, v146, v147, v148
	v_max3_f32 v90, v94, v90, v91
	v_max3_f32 v91, v188, v189, v186
	v_pk_fma_f32 v[108:109], v[108:109], s[36:37], v[160:161] op_sel_hi:[1,0,0]
	v_pk_fma_f32 v[106:107], v[106:107], s[36:37], v[160:161] op_sel_hi:[1,0,0]
	v_max3_f32 v93, v92, v93, v90
	v_max3_f32 v90, v184, v185, v182
	v_max_f32_e32 v95, v183, v187
	v_max3_f32 v91, v123, v127, v91
	v_pk_fma_f32 v[116:117], v[116:117], s[36:37], v[160:161] op_sel_hi:[1,0,0]
	v_pk_fma_f32 v[114:115], v[114:115], s[36:37], v[160:161] op_sel_hi:[1,0,0]
	v_max3_f32 v92, v124, v125, v122
	v_max3_f32 v94, v128, v129, v126
	v_max3_f32 v90, v95, v90, v91
	v_max3_f32 v91, v106, v107, v108
	v_pk_fma_f32 v[136:137], v[110:111], s[36:37], v[160:161] op_sel_hi:[1,0,0]
	v_pk_fma_f32 v[110:111], v[96:97], s[36:37], v[158:159] op_sel_hi:[1,0,0]
	v_max3_f32 v92, v92, v94, v90
	v_max3_f32 v90, v114, v115, v116
	v_max_f32_e32 v96, v117, v109
	v_max3_f32 v91, v131, v135, v91
	v_max3_f32 v94, v132, v133, v130
	v_max3_f32 v95, v136, v137, v134
	v_max3_f32 v90, v96, v90, v91
	v_pk_fma_f32 v[138:139], v[104:105], s[36:37], v[158:159] op_sel_hi:[1,0,0]
	v_pk_fma_f32 v[142:143], v[100:101], s[36:37], v[158:159] op_sel_hi:[1,0,0]
	v_max3_f32 v91, v94, v95, v90
	v_max3_f32 v95, v120, v121, v118
	v_pk_fma_f32 v[140:141], v[102:103], s[36:37], v[158:159] op_sel_hi:[1,0,0]
	v_pk_fma_f32 v[144:145], v[98:99], s[36:37], v[158:159] op_sel_hi:[1,0,0]
	v_max3_f32 v90, v112, v113, v110
	v_max_f32_e32 v98, v111, v119
	v_max3_f32 v95, v139, v143, v95
	v_max3_f32 v96, v140, v141, v138
	v_max3_f32 v97, v144, v145, v142
	v_max3_f32 v90, v98, v90, v95
	v_max3_f32 v94, v93, v92, v91
	v_max3_f32 v90, v96, v97, v90
	v_max_f32_e32 v94, v94, v90
	s_mov_b32 s23, 0x41000000
	v_cmp_lt_f32_e32 vcc, s23, v94
	s_or_b64 vcc, vcc, s[42:43]
	s_cbranch_vccz .LBB0_893
; template <int MODE> ...
;     ...
; #pragma unroll
;         for (int tt = 0; tt < 2; ++tt)
; #pragma unroll
;           for (int hh = 0; hh < 2; ++hh) {
;             float mx = mxq[tt][hh];
;             mx = fmaxf(mx, __shfl_xor(mx, 16));
;             mx = fmaxf(mx, __shfl_xor(mx, 32));
;             const float d = (mx == -INFINITY) ? 0.f : (first ? mx : fmaxf(mx, 0.f));
;             const float alpha = __builtin_amdgcn_exp2f(-d);
;             lsum[tt][hh] *= alpha;
;             nbias[tt][hh] -= d;
; #pragma unroll
;             for (int dt = 0; dt < 4; ++dt)
; #pragma unroll
;               for (int j = 0; j < 4; ++j) O[tt][hh][dt][j] *= alpha;
; #pragma unroll
;             for (int kh = 0; kh < 2; ++kh)
; #pragma unroll
;               for (int t = 0; t < 2; ++t) S[kh][tt][hh][t] = S[kh][tt][hh][t] - d;
;           }
	v_and_b32_e32 v95, 64, v226
	v_xor_b32_e32 v94, 16, v226
	v_add_u32_e32 v95, 64, v95
	v_cmp_lt_i32_e32 vcc, v94, v95
	s_nop 1
	v_cndmask_b32_e32 v94, v226, v94, vcc
	v_lshlrev_b32_e32 v96, 2, v94
	v_xor_b32_e32 v94, 32, v226
	v_cmp_lt_i32_e32 vcc, v94, v95
	s_nop 1
	v_cndmask_b32_e32 v94, v226, v94, vcc
	v_lshlrev_b32_e32 v97, 2, v94
	ds_bpermute_b32 v94, v96, v93
	v_max_f32_e32 v93, v93, v93
	s_waitcnt lgkmcnt(0)
	v_max_f32_e32 v94, v94, v94
	v_max_f32_e32 v93, v93, v94
	ds_bpermute_b32 v94, v97, v93
	s_waitcnt lgkmcnt(0)
	v_max_f32_e32 v94, v94, v94
	v_max_f32_e32 v93, v93, v94
	v_max_f32_e32 v94, 0, v93
	v_cndmask_b32_e64 v94, v94, v93, s[42:43]
	v_cmp_neq_f32_e32 vcc, s20, v93
	s_nop 1
	v_cndmask_b32_e32 v93, 0, v94, vcc
	v_exp_f32_e64 v94, -v93
	v_sub_f32_e32 v162, v162, v93
	v_sub_f32_e32 v176, v176, v93
	v_sub_f32_e32 v177, v177, v93
	v_sub_f32_e32 v174, v174, v93
	v_sub_f32_e32 v175, v175, v93
	v_sub_f32_e32 v180, v180, v93
	v_sub_f32_e32 v181, v181, v93
	v_sub_f32_e32 v178, v178, v93
	v_sub_f32_e32 v179, v179, v93
	v_sub_f32_e32 v150, v150, v93
	v_sub_f32_e32 v151, v151, v93
	v_sub_f32_e32 v152, v152, v93
	v_sub_f32_e32 v153, v153, v93
	v_sub_f32_e32 v146, v146, v93
	v_sub_f32_e32 v147, v147, v93
	v_sub_f32_e32 v148, v148, v93
	v_sub_f32_e32 v149, v149, v93
	ds_bpermute_b32 v93, v96, v92
	v_max_f32_e32 v92, v92, v92
	v_pk_mul_f32 v[72:73], v[72:73], v[94:95] op_sel_hi:[1,0]
	v_pk_mul_f32 v[70:71], v[70:71], v[94:95] op_sel_hi:[1,0]
	v_pk_mul_f32 v[80:81], v[80:81], v[94:95] op_sel_hi:[1,0]
	s_waitcnt lgkmcnt(0)
	v_max_f32_e32 v93, v93, v93
	v_max_f32_e32 v92, v92, v93
	ds_bpermute_b32 v93, v97, v92
	v_pk_mul_f32 v[78:79], v[78:79], v[94:95] op_sel_hi:[1,0]
	v_pk_mul_f32 v[64:65], v[64:65], v[94:95] op_sel_hi:[1,0]
	v_pk_mul_f32 v[62:63], v[62:63], v[94:95] op_sel_hi:[1,0]
	v_pk_mul_f32 v[76:77], v[76:77], v[94:95] op_sel_hi:[1,0]
	s_waitcnt lgkmcnt(0)
	v_max_f32_e32 v93, v93, v93
	v_max_f32_e32 v92, v92, v93
	v_max_f32_e32 v93, 0, v92
	v_cndmask_b32_e64 v93, v93, v92, s[42:43]
	v_cmp_neq_f32_e32 vcc, s20, v92
	v_pk_mul_f32 v[74:75], v[74:75], v[94:95] op_sel_hi:[1,0]
	s_nop 0
	v_cndmask_b32_e32 v93, 0, v93, vcc
	v_exp_f32_e64 v95, -v93
	v_sub_f32_e32 v164, v164, v93
	v_sub_f32_e32 v184, v184, v93
	v_sub_f32_e32 v185, v185, v93
	v_mov_b32_e32 v92, v95
	v_pk_mul_f32 v[88:89], v[88:89], v[92:93] op_sel_hi:[1,0]
	v_pk_mul_f32 v[86:87], v[86:87], v[92:93] op_sel_hi:[1,0]
	v_pk_mul_f32 v[68:69], v[68:69], v[92:93] op_sel_hi:[1,0]
	v_pk_mul_f32 v[66:67], v[66:67], v[92:93] op_sel_hi:[1,0]
	v_pk_mul_f32 v[60:61], v[60:61], v[92:93] op_sel_hi:[1,0]
	v_pk_mul_f32 v[58:59], v[58:59], v[92:93] op_sel_hi:[1,0]
	v_pk_mul_f32 v[84:85], v[84:85], v[92:93] op_sel_hi:[1,0]
	v_pk_mul_f32 v[82:83], v[82:83], v[92:93] op_sel_hi:[1,0]
	ds_bpermute_b32 v92, v96, v91
	v_max_f32_e32 v91, v91, v91
	v_sub_f32_e32 v182, v182, v93
	v_sub_f32_e32 v183, v183, v93
	v_sub_f32_e32 v188, v188, v93
	s_waitcnt lgkmcnt(0)
	v_max_f32_e32 v92, v92, v92
	v_max_f32_e32 v91, v91, v92
	ds_bpermute_b32 v92, v97, v91
	v_sub_f32_e32 v189, v189, v93
	v_sub_f32_e32 v186, v186, v93
	v_sub_f32_e32 v187, v187, v93
	v_sub_f32_e32 v124, v124, v93
	s_waitcnt lgkmcnt(0)
	v_max_f32_e32 v92, v92, v92
	v_max_f32_e32 v91, v91, v92
	v_max_f32_e32 v92, 0, v91
	v_cndmask_b32_e64 v92, v92, v91, s[42:43]
	v_cmp_neq_f32_e32 vcc, s20, v91
	v_sub_f32_e32 v125, v125, v93
	v_sub_f32_e32 v122, v122, v93
	v_cndmask_b32_e32 v91, 0, v92, vcc
	v_exp_f32_e64 v92, -v91
	v_sub_f32_e32 v160, v160, v91
	v_sub_f32_e32 v114, v114, v91
	v_sub_f32_e32 v115, v115, v91
	v_sub_f32_e32 v116, v116, v91
	v_sub_f32_e32 v117, v117, v91
	v_sub_f32_e32 v106, v106, v91
	v_sub_f32_e32 v107, v107, v91
	v_sub_f32_e32 v108, v108, v91
	v_sub_f32_e32 v109, v109, v91
	v_sub_f32_e32 v132, v132, v91
	v_sub_f32_e32 v133, v133, v91
	v_sub_f32_e32 v130, v130, v91
	v_sub_f32_e32 v131, v131, v91
	v_sub_f32_e32 v136, v136, v91
	v_sub_f32_e32 v137, v137, v91
	v_sub_f32_e32 v134, v134, v91
	v_sub_f32_e32 v135, v135, v91
	ds_bpermute_b32 v91, v96, v90
	v_max_f32_e32 v90, v90, v90
	v_sub_f32_e32 v123, v123, v93
	v_sub_f32_e32 v128, v128, v93
	v_sub_f32_e32 v129, v129, v93
	s_waitcnt lgkmcnt(0)
	v_max_f32_e32 v91, v91, v91
	v_max_f32_e32 v90, v90, v91
	ds_bpermute_b32 v91, v97, v90
	v_sub_f32_e32 v126, v126, v93
	v_sub_f32_e32 v127, v127, v93
	v_pk_mul_f32 v[44:45], v[44:45], v[92:93] op_sel_hi:[1,0]
	v_pk_mul_f32 v[42:43], v[42:43], v[92:93] op_sel_hi:[1,0]
	s_waitcnt lgkmcnt(0)
	v_max_f32_e32 v91, v91, v91
	v_max_f32_e32 v90, v90, v91
	v_max_f32_e32 v91, 0, v90
	v_cndmask_b32_e64 v91, v91, v90, s[42:43]
	v_cmp_neq_f32_e32 vcc, s20, v90
	v_pk_mul_f32 v[36:37], v[36:37], v[92:93] op_sel_hi:[1,0]
	v_pk_mul_f32 v[34:35], v[34:35], v[92:93] op_sel_hi:[1,0]
	v_cndmask_b32_e32 v91, 0, v91, vcc
	v_pk_mul_f32 v[12:13], v[12:13], v[92:93] op_sel_hi:[1,0]
	v_pk_mul_f32 v[10:11], v[10:11], v[92:93] op_sel_hi:[1,0]
	v_pk_mul_f32 v[8:9], v[8:9], v[92:93] op_sel_hi:[1,0]
	v_pk_mul_f32 v[6:7], v[6:7], v[92:93] op_sel_hi:[1,0]
	v_exp_f32_e64 v93, -v91
	v_pk_mul_f32 v[170:171], v[170:171], v[94:95]
	v_sub_f32_e32 v158, v158, v91
	v_sub_f32_e32 v112, v112, v91
	v_mov_b32_e32 v90, v93
	v_pk_mul_f32 v[156:157], v[156:157], v[92:93]
	v_pk_mul_f32 v[48:49], v[48:49], v[90:91] op_sel_hi:[1,0]
	v_pk_mul_f32 v[46:47], v[46:47], v[90:91] op_sel_hi:[1,0]
	v_pk_mul_f32 v[40:41], v[40:41], v[90:91] op_sel_hi:[1,0]
	v_pk_mul_f32 v[38:39], v[38:39], v[90:91] op_sel_hi:[1,0]
	v_pk_mul_f32 v[16:17], v[16:17], v[90:91] op_sel_hi:[1,0]
	v_pk_mul_f32 v[14:15], v[14:15], v[90:91] op_sel_hi:[1,0]
	v_pk_mul_f32 v[4:5], v[4:5], v[90:91] op_sel_hi:[1,0]
	v_pk_mul_f32 v[2:3], v[2:3], v[90:91] op_sel_hi:[1,0]
	v_sub_f32_e32 v113, v113, v91
	v_sub_f32_e32 v110, v110, v91
	v_sub_f32_e32 v111, v111, v91
	v_sub_f32_e32 v120, v120, v91
	v_sub_f32_e32 v121, v121, v91
	v_sub_f32_e32 v118, v118, v91
	v_sub_f32_e32 v119, v119, v91
	v_sub_f32_e32 v140, v140, v91
	v_sub_f32_e32 v141, v141, v91
	v_sub_f32_e32 v138, v138, v91
	v_sub_f32_e32 v139, v139, v91
	v_sub_f32_e32 v144, v144, v91
	v_sub_f32_e32 v145, v145, v91
	v_sub_f32_e32 v142, v142, v91
	v_sub_f32_e32 v143, v143, v91
